# phase 0 bf16 copy of h: the f32 source rows (read once) are loaded with the nt policy
# speedup vs baseline: 1.0263x; 1.0104x over previous
; DEVI uint32_t pk(float a, float b) { const hwf32x2 v = {a, b}; return __builtin_bit_cast(uint32_t, __builtin_convertvector(v, hwbf16x2)); }
; __device__ void phase_prep(const P& p, int vb, int nvb) {
;     ...
;   {
;     uint4* hb = (uint4*)(ws + WS_HB);
;     for (size_t i = gid; i < (size_t)NTOK * 128; i += gsz) {
;       const int prow = (int)(i >> 7), c = (int)(i & 127);
;       bool zf; const float* src = hrow_ptr(p, prow, zf);
;       uint4 o = make_uint4(0u, 0u, 0u, 0u);
;       if (!zf) { const float4 a = *(const float4*)(src + c * 8), b = *(const float4*)(src + c * 8 + 4); o = make_uint4(pk(a.x, a.y), pk(a.z, a.w), pk(b.x, b.y), pk(b.z, b.w)); }
;       hb[i] = o;
;     }
;   }
.LBB0_43:
	v_alignbit_b32 v2, v7, v6, 7
	v_mul_u32_u24_e32 v1, 0xf83f, v2
	v_lshrrev_b32_e32 v1, 28, v1
	v_mad_i32_i24 v2, v1, s18, v2
	v_cmp_lt_i32_e32 vcc, 15, v2
	s_and_saveexec_b64 s[16:17], vcc
	s_xor_b64 s[16:17], exec, s[16:17]
	v_lshlrev_b32_e32 v1, 12, v1
	v_add3_u32 v12, v2, v1, -16
	v_lshlrev_b64 v[4:5], 12, v[12:13]
	v_cmp_lt_u32_e64 s[14:15], s19, v2
	s_nop 1
	v_cndmask_b32_e64 v3, v5, 0, s[14:15]
	v_cndmask_b32_e64 v2, v4, 0, s[14:15]
	v_lshl_add_u64 v[14:15], s[60:61], 0, v[2:3]
	s_andn2_saveexec_b64 s[16:17], s[16:17]
	v_ashrrev_i32_e32 v3, 31, v2
	v_lshlrev_b64 v[2:3], 12, v[2:3]
	v_lshl_add_u64 v[14:15], s[62:63], 0, v[2:3]
	s_andn2_b64 s[14:15], s[14:15], exec
	s_or_b64 exec, exec, s[16:17]
	s_xor_b64 s[16:17], s[14:15], -1
	v_mov_b32_e32 v2, 0
	v_mov_b32_e32 v3, 0
	v_mov_b32_e32 v4, 0
	v_mov_b32_e32 v5, 0
	s_and_saveexec_b64 s[14:15], s[16:17]
	s_cbranch_execz .LBB0_42
	v_and_b32_e32 v1, 0x3f8, v10
	v_lshlrev_b32_e32 v12, 2, v1
	v_lshl_add_u64 v[14:15], v[14:15], 0, v[12:13]
	global_load_dwordx4 v[2:5], v[14:15], off nt
	s_nop 0
	global_load_dwordx4 v[14:17], v[14:15], off offset:16 nt
	s_waitcnt vmcnt(1)
	v_cvt_pk_bf16_f32 v2, v2, v3
	v_cvt_pk_bf16_f32 v3, v4, v5
	s_waitcnt vmcnt(0)
	v_cvt_pk_bf16_f32 v4, v14, v15
	v_cvt_pk_bf16_f32 v5, v16, v17
	s_branch .LBB0_42
